# layer-0 mixer-out phase: the context attention's 8 q-row loads (workgroups 0..23) issued together instead of 7 serialized round trips
# baseline (speedup 1.0000x reference)
; template <typename TQ> ...
;     ...
;   int tid_o = mk_tid(); asm volatile("" : "+v"(tid_o));
;   const int tid = tid_o, wid = tid >> 6, lane = tid & 63, r32 = lane & 31, hi = lane >> 5;
;   bf16* V_lds = (bf16*)lds; bf16* K_lds = (bf16*)(lds + NBUF * SHM_V);
;   float* ws = (float*)(lds + NBUF * SHM_V + NBUF * SHM_K) + wid * 64; float* li_l = ws; float* al_l = ws + 32;
;   float m_reg = -1e30f, l_reg = 0; f32x16 o[4] = {}; bf16x8 qr[8]; bool bounded = false;
;   const TQ* Qw = Qb + (long)(wid * QBLK + r32) * LDQ + hi * 8;
;   {
;     float x[8][8]; float ss = 0.f;
; #pragma unroll
;     for (int d0 = 0; d0 < 8; ++d0) { const u32x4 raw = *reinterpret_cast<const u32x4*>(Qw + d0 * 16);
; #pragma unroll
;       for (int q = 0; q < 4; ++q) { x[d0][2 * q] = __uint_as_float(raw[q] << 16); x[d0][2 * q + 1] = __uint_as_float(raw[q] & 0xffff0000u); } }
; __global__ void __launch_bounds__(NWAVES * 64, 2) mk_fwd(Args args) {
;     ...
;                     const int jx = bx, b = jx / 12, hq = jx % 12; const size_t qrow = (size_t)b * SB, kvoff = (size_t)(b * 4 + hq / 3) * SB * 128;
;                     attn::attn_dense_body<attn::bf16>((const attn::bf16*)(QB_ + qrow * 1536 + hq * 128), (const attn::bf16*)(KB_ + kvoff), (const attn::bf16*)(VB_ + kvoff), MIX_ + qrow * 2048 + 512 + hq * 128, 256, (char*)lds_raw, args.in[10], nullptr);
.LBB0_995:
	s_or_b64 exec, exec, s[0:1]
	v_readlane_b32 s0, v254, 34
	v_readlane_b32 s1, v254, 35
	s_add_u32 s8, s0, 0x9000
	s_addc_u32 s9, s1, 0
	s_cmp_gt_i32 s2, 23
	s_waitcnt lgkmcnt(0)
	s_barrier
	s_cbranch_scc1 .LBB0_1023
	s_mul_hi_i32 s1, s2, 0x2aaaaaab
	s_lshr_b32 s0, s1, 31
	s_ashr_i32 s4, s1, 1
	s_add_i32 s4, s4, s0
	s_mul_i32 s0, s4, 12
	s_sub_i32 s0, s2, s0
	s_mul_i32 s3, s0, 0x56
	s_lshr_b32 s5, s3, 8
	s_bfe_u32 s3, s3, 0x1000f
	s_add_i32 s5, s5, s3
	s_lshl_b32 s1, s4, 2
	s_sext_i32_i8 s3, s5
	s_add_i32 s1, s1, s3
	s_lshl_b32 s6, s0, 7
	s_ashr_i32 s7, s6, 31
	s_mul_i32 s5, s1, 0x210000
	s_mul_hi_i32 s3, s1, 0x210000
	s_add_u32 s0, s68, s5
	s_addc_u32 s1, s69, s3
	s_add_u32 s34, s66, s5
	s_addc_u32 s35, s67, s3
	s_mul_i32 s5, s4, 0x18c0000
	s_mul_hi_i32 s3, s4, 0x18c0000
	s_add_u32 s5, s77, s5
	s_addc_u32 s3, s76, s3
	s_lshl_b64 s[66:67], s[6:7], 1
	s_add_u32 s6, s5, s66
	s_addc_u32 s7, s3, s67
	s_getreg_b32 s3, hwreg(HW_REG_HW_ID, 0, 6)
	s_lshl_b32 s3, s3, 2
	s_and_b32 s3, s3, 0xfc
	s_or_b32 s3, s3, 0x27e00
	v_mov_b32_e32 v0, s3
	ds_read_b32 v0, v0
	v_mov_b32_e32 v163, 0
	s_waitcnt lgkmcnt(0)
	v_readfirstlane_b32 s3, v0
	v_mbcnt_lo_u32_b32 v0, -1, 0
	v_mbcnt_hi_u32_b32 v0, -1, v0
	s_nop 1
	v_lshl_add_u32 v161, s3, 6, v0
	s_movk_i32 s3, 0xc00
	v_ashrrev_i32_e32 v165, 6, v161
	v_and_b32_e32 v167, 31, v161
	v_lshlrev_b32_e32 v160, 5, v165
	v_bfe_u32 v168, v161, 5, 1
	v_or_b32_e32 v2, v160, v167
	v_mov_b64_e32 v[0:1], s[6:7]
	v_mad_i64_i32 v[0:1], s[6:7], v2, s3, v[0:1]
	v_lshlrev_b32_e32 v162, 4, v168
	v_lshl_add_u64 v[4:5], v[0:1], 0, v[162:163]
	global_load_dwordx4 v[0:3], v[4:5], off
	global_load_dwordx4 v[100:103], v[4:5], off offset:32
	global_load_dwordx4 v[104:107], v[4:5], off offset:64
	global_load_dwordx4 v[108:111], v[4:5], off offset:96
	global_load_dwordx4 v[112:115], v[4:5], off offset:128
	global_load_dwordx4 v[116:119], v[4:5], off offset:160
	global_load_dwordx4 v[120:123], v[4:5], off offset:192
	global_load_dwordx4 v[4:7], v[4:5], off offset:224
	s_mov_b32 s3, 0xf800000
	v_and_b32_e32 v166, 63, v161
	v_or_b32_e32 v34, 64, v162
	s_waitcnt vmcnt(7)
	v_lshlrev_b32_e32 v17, 16, v0
	v_and_b32_e32 v16, 0xffff0000, v0
	v_lshlrev_b32_e32 v15, 16, v1
	v_and_b32_e32 v14, 0xffff0000, v1
	v_lshlrev_b32_e32 v13, 16, v2
	v_and_b32_e32 v12, 0xffff0000, v2
	v_lshlrev_b32_e32 v11, 16, v3
	v_and_b32_e32 v10, 0xffff0000, v3

; template <typename TQ> ...
;     ...
;     for (int d0 = 0; d0 < 8; ++d0) { const u32x4 raw = *reinterpret_cast<const u32x4*>(Qw + d0 * 16);
; #pragma unroll
;       for (int q = 0; q < 4; ++q) { x[d0][2 * q] = __uint_as_float(raw[q] << 16); x[d0][2 * q + 1] = __uint_as_float(raw[q] & 0xffff0000u); } }
; #pragma unroll
;     for (int d0 = 0; d0 < 8; ++d0)
; #pragma unroll
;       for (int e = 0; e < 8; ++e) ss += x[d0][e] * x[d0][e];
	v_mul_f32_e32 v137, v16, v16
	v_fmac_f32_e32 v137, v17, v17
	v_fmac_f32_e32 v137, v15, v15
	v_fmac_f32_e32 v137, v14, v14
	v_fmac_f32_e32 v137, v13, v13
	v_fmac_f32_e32 v137, v12, v12
	v_fmac_f32_e32 v137, v11, v11
	v_fmac_f32_e32 v137, v10, v10
	s_waitcnt vmcnt(6)
	v_lshlrev_b32_e32 v25, 16, v100
	v_and_b32_e32 v24, 0xffff0000, v100
	v_lshlrev_b32_e32 v23, 16, v101
	v_and_b32_e32 v22, 0xffff0000, v101
	v_lshlrev_b32_e32 v21, 16, v102
	v_and_b32_e32 v20, 0xffff0000, v102
	v_lshlrev_b32_e32 v19, 16, v103
	v_and_b32_e32 v18, 0xffff0000, v103

; template <typename TQ> ...
;     ...
;     for (int d0 = 0; d0 < 8; ++d0) { const u32x4 raw = *reinterpret_cast<const u32x4*>(Qw + d0 * 16);
; #pragma unroll
;       for (int q = 0; q < 4; ++q) { x[d0][2 * q] = __uint_as_float(raw[q] << 16); x[d0][2 * q + 1] = __uint_as_float(raw[q] & 0xffff0000u); } }
; #pragma unroll
;     for (int d0 = 0; d0 < 8; ++d0)
; #pragma unroll
;       for (int e = 0; e < 8; ++e) ss += x[d0][e] * x[d0][e];
	v_fmac_f32_e32 v137, v25, v25
	v_fmac_f32_e32 v137, v24, v24
	v_fmac_f32_e32 v137, v23, v23
	v_fmac_f32_e32 v137, v22, v22
	v_fmac_f32_e32 v137, v21, v21
	v_fmac_f32_e32 v137, v20, v20
	v_fmac_f32_e32 v137, v19, v19
	v_fmac_f32_e32 v137, v18, v18
	s_waitcnt vmcnt(5)
	v_lshlrev_b32_e32 v33, 16, v104
	v_and_b32_e32 v32, 0xffff0000, v104
	v_lshlrev_b32_e32 v31, 16, v105
	v_and_b32_e32 v30, 0xffff0000, v105
	v_lshlrev_b32_e32 v29, 16, v106
	v_and_b32_e32 v28, 0xffff0000, v106
	v_lshlrev_b32_e32 v27, 16, v107
	v_and_b32_e32 v26, 0xffff0000, v107

; template <typename TQ> ...
;     ...
;     for (int d0 = 0; d0 < 8; ++d0) { const u32x4 raw = *reinterpret_cast<const u32x4*>(Qw + d0 * 16);
; #pragma unroll
;       for (int q = 0; q < 4; ++q) { x[d0][2 * q] = __uint_as_float(raw[q] << 16); x[d0][2 * q + 1] = __uint_as_float(raw[q] & 0xffff0000u); } }
; #pragma unroll
;     for (int d0 = 0; d0 < 8; ++d0)
; #pragma unroll
;       for (int e = 0; e < 8; ++e) ss += x[d0][e] * x[d0][e];
	v_fmac_f32_e32 v137, v33, v33
	v_fmac_f32_e32 v137, v32, v32
	v_fmac_f32_e32 v137, v31, v31
	v_fmac_f32_e32 v137, v30, v30
	v_fmac_f32_e32 v137, v29, v29
	v_fmac_f32_e32 v137, v28, v28
	v_fmac_f32_e32 v137, v27, v27
	v_fmac_f32_e32 v137, v26, v26
	s_waitcnt vmcnt(4)
	v_lshlrev_b32_e32 v42, 16, v108
	v_and_b32_e32 v41, 0xffff0000, v108
	v_lshlrev_b32_e32 v40, 16, v109
	v_and_b32_e32 v39, 0xffff0000, v109
	v_lshlrev_b32_e32 v38, 16, v110
	v_and_b32_e32 v37, 0xffff0000, v110
	v_lshlrev_b32_e32 v36, 16, v111
	v_and_b32_e32 v35, 0xffff0000, v111

; template <typename TQ> ...
;     ...
;     for (int d0 = 0; d0 < 8; ++d0) { const u32x4 raw = *reinterpret_cast<const u32x4*>(Qw + d0 * 16);
; #pragma unroll
;       for (int q = 0; q < 4; ++q) { x[d0][2 * q] = __uint_as_float(raw[q] << 16); x[d0][2 * q + 1] = __uint_as_float(raw[q] & 0xffff0000u); } }
; #pragma unroll
;     for (int d0 = 0; d0 < 8; ++d0)
; #pragma unroll
;       for (int e = 0; e < 8; ++e) ss += x[d0][e] * x[d0][e];
	v_fmac_f32_e32 v137, v42, v42
	v_fmac_f32_e32 v137, v41, v41
	v_fmac_f32_e32 v137, v40, v40
	v_fmac_f32_e32 v137, v39, v39
	v_fmac_f32_e32 v137, v38, v38
	v_fmac_f32_e32 v137, v37, v37
	v_fmac_f32_e32 v137, v36, v36
	v_fmac_f32_e32 v137, v35, v35
	s_waitcnt vmcnt(3)
	v_lshlrev_b32_e32 v50, 16, v112
	v_and_b32_e32 v49, 0xffff0000, v112
	v_lshlrev_b32_e32 v48, 16, v113
	v_and_b32_e32 v47, 0xffff0000, v113
	v_lshlrev_b32_e32 v46, 16, v114
	v_and_b32_e32 v45, 0xffff0000, v114
	v_lshlrev_b32_e32 v44, 16, v115
	v_and_b32_e32 v43, 0xffff0000, v115

; template <typename TQ> ...
;     ...
;     for (int d0 = 0; d0 < 8; ++d0) { const u32x4 raw = *reinterpret_cast<const u32x4*>(Qw + d0 * 16);
; #pragma unroll
;       for (int q = 0; q < 4; ++q) { x[d0][2 * q] = __uint_as_float(raw[q] << 16); x[d0][2 * q + 1] = __uint_as_float(raw[q] & 0xffff0000u); } }
; #pragma unroll
;     for (int d0 = 0; d0 < 8; ++d0)
; #pragma unroll
;       for (int e = 0; e < 8; ++e) ss += x[d0][e] * x[d0][e];
	v_fmac_f32_e32 v137, v50, v50
	v_fmac_f32_e32 v137, v49, v49
	v_fmac_f32_e32 v137, v48, v48
	v_fmac_f32_e32 v137, v47, v47
	v_fmac_f32_e32 v137, v46, v46
	v_fmac_f32_e32 v137, v45, v45
	v_fmac_f32_e32 v137, v44, v44
	v_fmac_f32_e32 v137, v43, v43
	s_waitcnt vmcnt(2)
	v_lshlrev_b32_e32 v58, 16, v116
	v_and_b32_e32 v57, 0xffff0000, v116
	v_lshlrev_b32_e32 v56, 16, v117
	v_and_b32_e32 v55, 0xffff0000, v117
	v_lshlrev_b32_e32 v54, 16, v118
	v_and_b32_e32 v53, 0xffff0000, v118
	v_lshlrev_b32_e32 v52, 16, v119
	v_and_b32_e32 v51, 0xffff0000, v119

; template <typename TQ> ...
;     ...
;     for (int d0 = 0; d0 < 8; ++d0) { const u32x4 raw = *reinterpret_cast<const u32x4*>(Qw + d0 * 16);
; #pragma unroll
;       for (int q = 0; q < 4; ++q) { x[d0][2 * q] = __uint_as_float(raw[q] << 16); x[d0][2 * q + 1] = __uint_as_float(raw[q] & 0xffff0000u); } }
; #pragma unroll
;     for (int d0 = 0; d0 < 8; ++d0)
; #pragma unroll
;       for (int e = 0; e < 8; ++e) ss += x[d0][e] * x[d0][e];
	v_fmac_f32_e32 v137, v58, v58

; template <typename TQ> ...
;     ...
;       for (int q = 0; q < 4; ++q) { x[d0][2 * q] = __uint_as_float(raw[q] << 16); x[d0][2 * q + 1] = __uint_as_float(raw[q] & 0xffff0000u); } }
; #pragma unroll
;     for (int d0 = 0; d0 < 8; ++d0)
; #pragma unroll
;       for (int e = 0; e < 8; ++e) ss += x[d0][e] * x[d0][e];
;     ss += __shfl_xor(ss, 32);
;     const float rs = 1.f / sqrtf(ss * (1.f / 128.f) + 1e-6f);
; #pragma unroll
;     for (int d0 = 0; d0 < 8; ++d0) { const float* gp = qgain + 16 * d0 + 8 * hi; const f32x8 g = *reinterpret_cast<const f32x8*>(gp);
; #pragma unroll
;       for (int e = 0; e < 8; ++e) x[d0][e] *= rs * g[e]; }
	v_fmac_f32_e32 v137, v57, v57
	v_fmac_f32_e32 v137, v56, v56
	v_fmac_f32_e32 v137, v55, v55
	v_fmac_f32_e32 v137, v54, v54
	v_fmac_f32_e32 v137, v53, v53
	v_fmac_f32_e32 v137, v52, v52
	v_fmac_f32_e32 v137, v51, v51
	s_waitcnt vmcnt(1)
	v_lshlrev_b32_e32 v66, 16, v120
	v_and_b32_e32 v65, 0xffff0000, v120
	v_xor_b32_e32 v0, 32, v184
	v_cmp_lt_i32_e32 vcc, v0, v185
	s_waitcnt vmcnt(0)
	v_lshlrev_b32_e32 v67, 16, v4
	v_and_b32_e32 v136, 0xffff0000, v4
	v_cndmask_b32_e32 v0, v184, v0, vcc
	v_and_b32_e32 v4, 32, v161
	v_lshlrev_b32_e32 v64, 16, v121
	v_and_b32_e32 v63, 0xffff0000, v121
	v_lshlrev_b32_e32 v62, 16, v122
	v_and_b32_e32 v61, 0xffff0000, v122
	v_lshlrev_b32_e32 v60, 16, v123
	v_and_b32_e32 v59, 0xffff0000, v123
	v_and_b32_e32 v8, 0xffff0000, v7
	v_lshlrev_b32_e32 v9, 16, v7
	v_lshlrev_b32_e32 v7, 2, v0
	global_load_dwordx4 v[68:71], v4, s[20:21] offset:16
	global_load_dwordx4 v[72:75], v4, s[20:21]
	global_load_dwordx4 v[76:79], v4, s[20:21] offset:80
	global_load_dwordx4 v[80:83], v4, s[20:21] offset:64
	global_load_dwordx4 v[84:87], v4, s[20:21] offset:144
	global_load_dwordx4 v[88:91], v4, s[20:21] offset:128
	global_load_dwordx4 v[92:95], v4, s[20:21] offset:208
	global_load_dwordx4 v[96:99], v4, s[20:21] offset:192
	global_load_dwordx4 v[100:103], v4, s[20:21] offset:272
	global_load_dwordx4 v[104:107], v4, s[20:21] offset:256
	global_load_dwordx4 v[108:111], v4, s[20:21] offset:336
	global_load_dwordx4 v[112:115], v4, s[20:21] offset:320
	global_load_dwordx4 v[116:119], v4, s[20:21] offset:400
	global_load_dwordx4 v[120:123], v4, s[20:21] offset:384
	global_load_dwordx4 v[0:3], v4, s[20:21] offset:464
	global_load_dwordx4 v[124:127], v4, s[20:21] offset:448
	v_fmac_f32_e32 v137, v66, v66
	v_fmac_f32_e32 v137, v65, v65
	v_fmac_f32_e32 v137, v64, v64
	v_fmac_f32_e32 v137, v63, v63
	v_fmac_f32_e32 v137, v62, v62
	v_fmac_f32_e32 v137, v61, v61
	v_fmac_f32_e32 v137, v60, v60
	v_fmac_f32_e32 v137, v59, v59
	v_fmac_f32_e32 v137, v67, v67
	v_and_b32_e32 v135, 0xffff0000, v5
	v_lshlrev_b32_e32 v134, 16, v5
	v_fmac_f32_e32 v137, v136, v136
	v_pk_mul_f32 v[4:5], v[134:135], v[134:135]
	v_and_b32_e32 v131, 0xffff0000, v6
	v_lshlrev_b32_e32 v130, 16, v6
	v_add_f32_e32 v4, v4, v137
	v_pk_mul_f32 v[132:133], v[130:131], v[130:131]
	v_add_f32_e32 v4, v5, v4
	v_add_f32_e32 v4, v132, v4
	v_pk_mul_f32 v[128:129], v[8:9], v[8:9]
	v_add_f32_e32 v4, v133, v4
	v_add_f32_e32 v4, v129, v4
	v_add_f32_e32 v4, v128, v4
	ds_bpermute_b32 v5, v7, v4
	s_waitcnt lgkmcnt(0)
	v_add_f32_e32 v4, v4, v5
	v_mov_b32_e32 v5, 0x358637bd
	v_fmac_f32_e32 v5, 0x3c000000, v4
	v_cmp_gt_f32_e32 vcc, s3, v5
	v_mul_f32_e32 v4, 0x4f800000, v5
	s_nop 0
	v_cndmask_b32_e32 v4, v5, v4, vcc
	v_sqrt_f32_e32 v5, v4
	s_nop 0
	v_add_u32_e32 v6, -1, v5
	v_fma_f32 v128, -v6, v5, v4
	v_cmp_ge_f32_e64 s[40:41], 0, v128
	v_add_u32_e32 v128, 1, v5
	s_nop 0
	v_cndmask_b32_e64 v6, v5, v6, s[40:41]
	v_fma_f32 v5, -v128, v5, v4
	v_cmp_lt_f32_e64 s[40:41], 0, v5
	s_nop 1
	v_cndmask_b32_e64 v5, v6, v128, s[40:41]
	v_mul_f32_e32 v6, 0x37800000, v5
	v_cndmask_b32_e32 v6, v5, v6, vcc
	v_mov_b32_e32 v5, 0x260
	v_cmp_class_f32_e32 vcc, v4, v5
	s_nop 1
	v_cndmask_b32_e32 v4, v6, v4, vcc
	v_div_scale_f32 v6, s[6:7], v4, v4, 1.0
	v_rcp_f32_e32 v128, v6
	s_nop 0
	v_fma_f32 v129, -v6, v128, 1.0
	v_fmac_f32_e32 v128, v129, v128
	v_div_scale_f32 v129, vcc, 1.0, v4, 1.0
	v_mul_f32_e32 v132, v129, v128
	v_fma_f32 v133, -v6, v132, v129
	v_fmac_f32_e32 v132, v133, v128
	v_fma_f32 v6, -v6, v132, v129
	v_div_fmas_f32 v6, v6, v128, v132
	v_div_fixup_f32 v4, v6, v4, 1.0
	s_waitcnt vmcnt(14)
	v_mul_f32_e32 v6, v72, v4
	v_mul_f32_e32 v6, v6, v17
	v_mul_f32_e32 v17, v73, v4
	v_mul_f32_e32 v16, v17, v16
	v_mul_f32_e32 v17, v74, v4
	v_mul_f32_e32 v15, v17, v15
	v_mul_f32_e32 v17, v75, v4
	v_mul_f32_e32 v14, v17, v14
	v_mul_f32_e32 v17, v68, v4
	v_mul_f32_e32 v13, v17, v13
	v_mul_f32_e32 v17, v69, v4
	v_mul_f32_e32 v12, v17, v12
	v_mul_f32_e32 v17, v70, v4
	v_mul_f32_e32 v17, v17, v11
	v_mul_f32_e32 v11, v71, v4
	v_mul_f32_e32 v68, v11, v10
	s_waitcnt vmcnt(12)
	v_mul_f32_e32 v10, v80, v4
	v_mul_f32_e32 v25, v10, v25
	v_mul_f32_e32 v10, v81, v4
	v_mul_f32_e32 v24, v10, v24
	v_mul_f32_e32 v10, v82, v4
	v_mul_f32_e32 v23, v10, v23
	v_mul_f32_e32 v10, v83, v4
	v_mul_f32_e32 v22, v10, v22
	v_mul_f32_e32 v10, v76, v4
	v_mul_f32_e32 v21, v10, v21
	v_mul_f32_e32 v10, v77, v4
	v_mul_f32_e32 v20, v10, v20
	v_mul_f32_e32 v10, v78, v4
	v_mul_f32_e32 v19, v10, v19
	v_mul_f32_e32 v10, v79, v4
	v_mul_f32_e32 v18, v10, v18
	s_waitcnt vmcnt(10)
	v_mul_f32_e32 v10, v88, v4
	v_mul_f32_e32 v33, v10, v33
	v_mul_f32_e32 v10, v89, v4
	v_mul_f32_e32 v32, v10, v32
	v_mul_f32_e32 v10, v90, v4
	v_mul_f32_e32 v31, v10, v31
	v_mul_f32_e32 v10, v91, v4
	v_mul_f32_e32 v71, 0x3e0293ee, v16
	v_mul_f32_e32 v16, v16, v16
	v_mul_f32_e32 v30, v10, v30
	v_mul_f32_e32 v10, v84, v4
	v_fmac_f32_e32 v16, v6, v6
	v_mul_f32_e32 v29, v10, v29
	v_mul_f32_e32 v10, v85, v4
	v_fmac_f32_e32 v16, v15, v15
	v_mul_f32_e32 v28, v10, v28
	v_mul_f32_e32 v10, v86, v4
	v_fmac_f32_e32 v16, v14, v14
	v_mul_f32_e32 v27, v10, v27
	v_mul_f32_e32 v10, v87, v4
	v_fmac_f32_e32 v16, v13, v13
	v_mul_f32_e32 v26, v10, v26
	s_waitcnt vmcnt(8)
	v_mul_f32_e32 v10, v96, v4
	v_fmac_f32_e32 v16, v12, v12
	v_mul_f32_e32 v42, v10, v42
	v_mul_f32_e32 v10, v97, v4
	v_fmac_f32_e32 v16, v17, v17
	v_mul_f32_e32 v41, v10, v41
	v_mul_f32_e32 v10, v98, v4
	v_fmac_f32_e32 v16, v68, v68
	v_mul_f32_e32 v40, v10, v40
	v_mul_f32_e32 v10, v99, v4
	v_fmac_f32_e32 v16, v25, v25
	v_mul_f32_e32 v39, v10, v39
	v_mul_f32_e32 v10, v92, v4
	v_fmac_f32_e32 v16, v24, v24
	v_mul_f32_e32 v38, v10, v38
	v_mul_f32_e32 v10, v93, v4
	v_fmac_f32_e32 v16, v23, v23
	v_mul_f32_e32 v37, v10, v37
	v_mul_f32_e32 v10, v94, v4
	v_fmac_f32_e32 v16, v22, v22
	v_mul_f32_e32 v36, v10, v36
	v_mul_f32_e32 v10, v95, v4
	v_fmac_f32_e32 v16, v21, v21
	v_mul_f32_e32 v35, v10, v35
	s_waitcnt vmcnt(6)
; template <typename TQ> ...
;     ...
;       for (int e = 0; e < 8; ++e) x[d0][e] *= rs * g[e]; }
;     if (rope_blk) {
;       const float* rp = rope_blk + (long)(wid * QBLK + r32) * 128;
; #pragma unroll
;       for (int a = 0; a < 2; ++a)
; #pragma unroll
;         for (int dd = 0; dd < 2; ++dd) { const float* cp = rp + 2 * (a * 32 + 16 * dd + 8 * hi);
; #pragma unroll
;           for (int e4 = 0; e4 < 4; ++e4) { const f32x4v cs = *reinterpret_cast<const f32x4v*>(cp + 4 * e4);
; #pragma unroll
;             for (int u = 0; u < 2; ++u) { const int e = 2 * e4 + u; const float c = cs[2 * u], sn = cs[2 * u + 1], x1 = x[4 * a + dd][e], x2 = x[4 * a + 2 + dd][e];
;               x[4 * a + dd][e] = x1 * c - x2 * sn; x[4 * a + 2 + dd][e] = x1 * sn + x2 * c; } } }
;     }
; #pragma unroll
;     for (int d0 = 0; d0 < 8; ++d0) { constexpr float Cq = SCALE * 1.4426950408889634f;
;       u32x4 w = {cvtpk(x[d0][0] * Cq, x[d0][1] * Cq), cvtpk(x[d0][2] * Cq, x[d0][3] * Cq), cvtpk(x[d0][4] * Cq, x[d0][5] * Cq), cvtpk(x[d0][6] * Cq, x[d0][7] * Cq)}; qr[d0] = *reinterpret_cast<bf16x8*>(&w); }
;     float q2 = 0.f;
; #pragma unroll
;     for (int d0 = 0; d0 < 8; ++d0)
; #pragma unroll
;       for (int e = 0; e < 8; ++e) q2 += x[d0][e] * x[d0][e];
	v_mul_f32_e32 v10, v104, v4
	v_fmac_f32_e32 v16, v20, v20
	v_mul_f32_e32 v50, v10, v50
	v_mul_f32_e32 v10, v105, v4
	v_fmac_f32_e32 v16, v19, v19
	v_mul_f32_e32 v49, v10, v49
	v_mul_f32_e32 v10, v106, v4
	v_fmac_f32_e32 v16, v18, v18
	v_mul_f32_e32 v48, v10, v48
	v_mul_f32_e32 v10, v107, v4
	v_fmac_f32_e32 v16, v33, v33
	v_mul_f32_e32 v47, v10, v47
	v_mul_f32_e32 v10, v100, v4
	v_fmac_f32_e32 v16, v32, v32
	v_mul_f32_e32 v46, v10, v46
	v_mul_f32_e32 v10, v101, v4
	v_fmac_f32_e32 v16, v31, v31
	v_mul_f32_e32 v45, v10, v45
	v_mul_f32_e32 v10, v102, v4
	v_fmac_f32_e32 v16, v30, v30
	v_mul_f32_e32 v44, v10, v44
	v_mul_f32_e32 v10, v103, v4
	v_fmac_f32_e32 v16, v29, v29
	v_mul_f32_e32 v43, v10, v43
	s_waitcnt vmcnt(4)
	v_mul_f32_e32 v10, v112, v4
	v_fmac_f32_e32 v16, v28, v28
	v_mul_f32_e32 v58, v10, v58
	v_mul_f32_e32 v10, v113, v4
	v_fmac_f32_e32 v16, v27, v27
	v_mul_f32_e32 v57, v10, v57
	v_mul_f32_e32 v10, v114, v4
	v_fmac_f32_e32 v16, v26, v26
	v_mul_f32_e32 v56, v10, v56
	v_mul_f32_e32 v10, v115, v4
	v_fmac_f32_e32 v16, v42, v42
	v_mul_f32_e32 v55, v10, v55
	v_mul_f32_e32 v10, v108, v4
	v_fmac_f32_e32 v16, v41, v41
	v_mul_f32_e32 v54, v10, v54
	v_mul_f32_e32 v10, v109, v4
	v_fmac_f32_e32 v16, v40, v40
	v_mul_f32_e32 v53, v10, v53
	v_mul_f32_e32 v10, v110, v4
	v_fmac_f32_e32 v16, v39, v39
	v_mul_f32_e32 v52, v10, v52
	v_mul_f32_e32 v10, v111, v4
	v_mul_f32_e32 v70, 0x3e0293ee, v6
	v_fmac_f32_e32 v16, v38, v38
	v_mul_f32_e32 v51, v10, v51
	s_waitcnt vmcnt(2)
	v_mul_f32_e32 v10, v120, v4
	v_cvt_pk_bf16_f32 v112, v70, v71
	v_mul_f32_e32 v70, 0x3e0293ee, v15
	v_mul_f32_e32 v71, 0x3e0293ee, v14
	v_fmac_f32_e32 v16, v37, v37
	v_mul_f32_e32 v66, v10, v66
	v_mul_f32_e32 v10, v121, v4
	v_cvt_pk_bf16_f32 v113, v70, v71
	v_mul_f32_e32 v70, 0x3e0293ee, v13
	v_mul_f32_e32 v71, 0x3e0293ee, v12
	v_fmac_f32_e32 v16, v36, v36
	v_mul_f32_e32 v65, v10, v65
	v_mul_f32_e32 v10, v122, v4
	v_cvt_pk_bf16_f32 v114, v70, v71
	v_mul_f32_e32 v70, 0x3e0293ee, v17
	v_mul_f32_e32 v71, 0x3e0293ee, v68
	v_fmac_f32_e32 v16, v35, v35
	v_mul_f32_e32 v64, v10, v64
	v_mul_f32_e32 v10, v123, v4
	v_cvt_pk_bf16_f32 v115, v70, v71
	v_mul_f32_e32 v70, 0x3e0293ee, v25
	v_mul_f32_e32 v71, 0x3e0293ee, v24
	v_fmac_f32_e32 v16, v50, v50
	v_mul_f32_e32 v63, v10, v63
	v_mul_f32_e32 v10, v116, v4
	v_cvt_pk_bf16_f32 v116, v70, v71
	v_mul_f32_e32 v70, 0x3e0293ee, v23
	v_mul_f32_e32 v71, 0x3e0293ee, v22
	v_fmac_f32_e32 v16, v49, v49
	v_mul_f32_e32 v62, v10, v62
	v_mul_f32_e32 v10, v117, v4
	v_cvt_pk_bf16_f32 v117, v70, v71
	v_mul_f32_e32 v70, 0x3e0293ee, v21
	v_mul_f32_e32 v71, 0x3e0293ee, v20
	v_fmac_f32_e32 v16, v48, v48
	v_mul_f32_e32 v61, v10, v61
	v_mul_f32_e32 v10, v118, v4
	v_cvt_pk_bf16_f32 v118, v70, v71
	v_mul_f32_e32 v70, 0x3e0293ee, v19
	v_mul_f32_e32 v71, 0x3e0293ee, v18
	v_fmac_f32_e32 v16, v47, v47
	v_mul_f32_e32 v60, v10, v60
	v_mul_f32_e32 v10, v119, v4
	v_cvt_pk_bf16_f32 v119, v70, v71
	v_mul_f32_e32 v70, 0x3e0293ee, v33
	v_mul_f32_e32 v71, 0x3e0293ee, v32
	v_fmac_f32_e32 v16, v46, v46
	v_cvt_pk_bf16_f32 v120, v70, v71
	v_mul_f32_e32 v70, 0x3e0293ee, v31
	v_mul_f32_e32 v71, 0x3e0293ee, v30
	v_fmac_f32_e32 v16, v45, v45
	v_cvt_pk_bf16_f32 v121, v70, v71
	v_mul_f32_e32 v70, 0x3e0293ee, v29
	v_mul_f32_e32 v71, 0x3e0293ee, v28
	v_fmac_f32_e32 v16, v44, v44
	v_cvt_pk_bf16_f32 v122, v70, v71
	v_mul_f32_e32 v70, 0x3e0293ee, v27
	v_mul_f32_e32 v71, 0x3e0293ee, v26
	v_fmac_f32_e32 v16, v43, v43
	v_cvt_pk_bf16_f32 v123, v70, v71
	v_mul_f32_e32 v70, 0x3e0293ee, v42
	v_mul_f32_e32 v71, 0x3e0293ee, v41
	v_fmac_f32_e32 v16, v58, v58
	v_mul_f32_e32 v59, v10, v59
	s_waitcnt vmcnt(0)
	v_mul_f32_e32 v10, v124, v4
	v_cvt_pk_bf16_f32 v124, v70, v71
	v_mul_f32_e32 v70, 0x3e0293ee, v40
	v_mul_f32_e32 v71, 0x3e0293ee, v39
	v_fmac_f32_e32 v16, v57, v57
	v_mul_f32_e32 v67, v10, v67
	v_mul_f32_e32 v10, v125, v4
	v_cvt_pk_bf16_f32 v125, v70, v71
	v_mul_f32_e32 v70, 0x3e0293ee, v38
	v_mul_f32_e32 v71, 0x3e0293ee, v37
	v_fmac_f32_e32 v16, v56, v56
	v_mul_f32_e32 v69, v10, v136
	v_pk_mul_f32 v[10:11], v[126:127], v[4:5] op_sel_hi:[1,0]
	v_cvt_pk_bf16_f32 v126, v70, v71
	v_mul_f32_e32 v70, 0x3e0293ee, v36
	v_mul_f32_e32 v71, 0x3e0293ee, v35
	v_fmac_f32_e32 v16, v55, v55
	v_cvt_pk_bf16_f32 v127, v70, v71
	v_mul_f32_e32 v70, 0x3e0293ee, v50
	v_mul_f32_e32 v71, 0x3e0293ee, v49
	v_fmac_f32_e32 v16, v54, v54
	v_cvt_pk_bf16_f32 v128, v70, v71
	v_mul_f32_e32 v70, 0x3e0293ee, v48
	v_mul_f32_e32 v71, 0x3e0293ee, v47
	v_fmac_f32_e32 v16, v53, v53
	v_pk_mul_f32 v[0:1], v[0:1], v[4:5] op_sel_hi:[1,0]
	v_cvt_pk_bf16_f32 v129, v70, v71
	v_mul_f32_e32 v70, 0x3e0293ee, v46
	v_mul_f32_e32 v71, 0x3e0293ee, v45
	v_fmac_f32_e32 v16, v52, v52
	v_pk_mul_f32 v[0:1], v[0:1], v[130:131]
	v_cvt_pk_bf16_f32 v130, v70, v71
	v_mul_f32_e32 v70, 0x3e0293ee, v44
	v_mul_f32_e32 v71, 0x3e0293ee, v43
	v_fmac_f32_e32 v16, v51, v51
	v_cvt_pk_bf16_f32 v131, v70, v71
	v_mul_f32_e32 v70, 0x3e0293ee, v58
	v_mul_f32_e32 v71, 0x3e0293ee, v57
	v_fmac_f32_e32 v16, v66, v66
	v_cvt_pk_bf16_f32 v132, v70, v71
	v_mul_f32_e32 v70, 0x3e0293ee, v56
	v_mul_f32_e32 v71, 0x3e0293ee, v55
	v_fmac_f32_e32 v16, v65, v65
	v_cvt_pk_bf16_f32 v133, v70, v71
	v_mul_f32_e32 v70, 0x3e0293ee, v54
	v_mul_f32_e32 v71, 0x3e0293ee, v53
	v_fmac_f32_e32 v16, v64, v64
	v_pk_mul_f32 v[10:11], v[10:11], v[134:135]
	v_cvt_pk_bf16_f32 v134, v70, v71
	v_mul_f32_e32 v70, 0x3e0293ee, v52
	v_mul_f32_e32 v71, 0x3e0293ee, v51
	v_fmac_f32_e32 v16, v63, v63
	v_cvt_pk_bf16_f32 v135, v70, v71
	v_mul_f32_e32 v70, 0x3e0293ee, v66
	v_mul_f32_e32 v71, 0x3e0293ee, v65
	v_fmac_f32_e32 v16, v62, v62
	v_cvt_pk_bf16_f32 v136, v70, v71
	v_mul_f32_e32 v70, 0x3e0293ee, v64
	v_mul_f32_e32 v71, 0x3e0293ee, v63
; __device__ __forceinline__ int v_st(int k, int c) { const int kk = (k & ~0xC) | ((k & 4) << 1) | ((k & 8) >> 1); return ((kk >> 3) * 4 + (c >> 5)) * 512 + ((kk & 7) * 32 + (c & 31)) * 2; }
; __device__ __forceinline__ int v_rd_base(int lane) { return ((lane & 3) << 3) | (((lane >> 2) & 3) << 6) | (((lane >> 4) & 1) << 5) | (((lane >> 5) & 1) << 8); }
; #define SLOAD(i, k0) do { sr_[i].vs0 = St::ld8(&Vh[(long)((k0) + sr) * LDK + sc]); sr_[i].vs1 = St::ld8(&Vh[(long)((k0) + 32 + sr) * LDK + sc]); \
;     sr_[i].ks0 = St::ld8(&Kh[(long)((k0) + sr) * LDK + sc]); sr_[i].ks1 = St::ld8(&Kh[(long)((k0) + 32 + sr) * LDK + sc]); } while (0)
; #define SWAIT() do { if constexpr (SDEPTH == 2) asm volatile("s_waitcnt vmcnt(4)" ::: "memory"); else asm volatile("s_waitcnt vmcnt(0)" ::: "memory"); } while (0)
; template <typename TQ> ...
;     ...
;     float q2 = 0.f;
; #pragma unroll
;     for (int d0 = 0; d0 < 8; ++d0)
; #pragma unroll
;       for (int e = 0; e < 8; ++e) q2 += x[d0][e] * x[d0][e];
;     q2 += __shfl_xor(q2, 32);
;     float gk = fmaxf(fabsf(qgain[128 + lane]), fabsf(qgain[192 + lane]));
; #pragma unroll
;     for (int s = 1; s < 64; s <<= 1) gk = fmaxf(gk, __shfl_xor(gk, s));
;     constexpr float C = SCALE * 1.4426950408889634f;
;     const float Bp = sqrtf(q2) * 11.313708498984761f * gk * 1.02f * C;
;     bounded = __all(Bp < 60.f) != 0;
;     if (bounded) m_reg = 0.f;
;   }
;   const int sr = tid >> 4, sc = (tid & 15) * 8, vst0 = v_st(sr, sc), vst1 = v_st(32 + sr, sc);
;   const int vb0 = (int)(uintptr_t)V_lds + v_rd_base(lane);
;   struct { typename St::T vs0, vs1, ks0, ks1; } sr_[SDEPTH];
;     ...
;   f32x16 pA0, pA1, pB0, pB1; float mnA, mnB, alA, alB; bf16x8 pa0, pa1, pa2, pa3; const int NT = seq / KVBLK;
;   static_assert(SHM_V == SHM_K, "one buffer offset serves K and V");
;   constexpr int SE = 0, SO = SDEPTH - 1;
;   SLOAD(SE, 0); asm volatile("s_waitcnt vmcnt(0)" ::: "memory"); SWRITE(0, SE); __syncthreads();
;   qkt(pA0, pA1, K_lds, qr, r32, hi); partialSM(pA0, pA1, m_reg, mnA, alA, bounded);
;   SLOAD(SO, KVBLK); if constexpr (SDEPTH == 2) { if (2 < NT) SLOAD(SE, 2 * KVBLK); }
;   SWAIT(); SWRITE((int)SHM_K, SO); __syncthreads();
	v_fmac_f32_e32 v16, v61, v61
	v_cvt_pk_bf16_f32 v137, v70, v71
	v_mul_f32_e32 v70, 0x3e0293ee, v62
	v_mul_f32_e32 v71, 0x3e0293ee, v61
	v_fmac_f32_e32 v16, v60, v60
	v_cvt_pk_bf16_f32 v138, v70, v71
	v_mul_f32_e32 v70, 0x3e0293ee, v60
	v_mul_f32_e32 v71, 0x3e0293ee, v59
	v_fmac_f32_e32 v16, v59, v59
	v_cvt_pk_bf16_f32 v139, v70, v71
	v_mul_f32_e32 v70, 0x3e0293ee, v67
	v_mul_f32_e32 v71, 0x3e0293ee, v69
	v_fmac_f32_e32 v16, v67, v67
	v_cvt_pk_bf16_f32 v140, v70, v71
	v_mul_f32_e32 v70, 0x3e0293ee, v10
	v_mul_f32_e32 v71, 0x3e0293ee, v11
	v_fmac_f32_e32 v16, v69, v69
	v_pk_mul_f32 v[10:11], v[10:11], v[10:11]
	v_cvt_pk_bf16_f32 v141, v70, v71
	v_mul_f32_e32 v70, 0x3e0293ee, v0
	v_add_f32_e32 v6, v10, v16
	v_mul_f32_e32 v71, 0x3e0293ee, v1
	v_add_f32_e32 v6, v11, v6
	v_pk_mul_f32 v[0:1], v[0:1], v[0:1]
	v_cvt_pk_bf16_f32 v142, v70, v71
	v_cmp_lt_i32_e32 vcc, v188, v185
	v_add_f32_e32 v0, v0, v6
	v_add_f32_e32 v6, v1, v0
	v_pk_mul_f32 v[0:1], v[2:3], v[4:5] op_sel:[1,0] op_sel_hi:[0,0]
	v_pk_mul_f32 v[0:1], v[0:1], v[8:9]
	v_lshlrev_b32_e32 v44, 8, v167
	v_mul_f32_e32 v2, 0x3e0293ee, v1
	v_mul_f32_e32 v3, 0x3e0293ee, v0
	v_cvt_pk_bf16_f32 v143, v2, v3
	v_lshlrev_b32_e32 v2, 2, v166
	global_load_dword v3, v2, s[20:21] offset:512
	s_nop 0
	global_load_dword v2, v2, s[20:21] offset:768
	v_pk_mul_f32 v[0:1], v[0:1], v[0:1]
	v_or_b32_e32 v36, 32, v162
	v_add_f32_e32 v1, v1, v6
	v_add_f32_e32 v0, v0, v1
	ds_bpermute_b32 v1, v7, v0
	s_waitcnt lgkmcnt(0)
	v_add_f32_e32 v0, v0, v1
	v_mul_f32_e32 v1, 0x4f800000, v0
	s_waitcnt vmcnt(1)
	v_max_f32_e64 v3, |v3|, |v3|
	s_waitcnt vmcnt(0)
	v_max_f32_e64 v2, |v2|, |v2|
	v_max_f32_e32 v2, v3, v2
	v_cndmask_b32_e32 v3, v184, v188, vcc
	v_lshlrev_b32_e32 v3, 2, v3
	ds_bpermute_b32 v3, v3, v2
	v_cmp_lt_i32_e32 vcc, v189, v185
	s_waitcnt lgkmcnt(0)
	v_max_f32_e32 v3, v3, v3
	v_max_f32_e32 v2, v2, v3
	v_cndmask_b32_e32 v3, v184, v189, vcc
	v_lshlrev_b32_e32 v3, 2, v3
	ds_bpermute_b32 v3, v3, v2
	v_cmp_lt_i32_e32 vcc, v187, v185
	s_waitcnt lgkmcnt(0)
	v_max_f32_e32 v3, v3, v3
	v_max_f32_e32 v2, v2, v3
	v_cndmask_b32_e32 v3, v184, v187, vcc
	v_lshlrev_b32_e32 v3, 2, v3
	ds_bpermute_b32 v3, v3, v2
	v_cmp_lt_i32_e32 vcc, v186, v185
	s_waitcnt lgkmcnt(0)
	v_max_f32_e32 v3, v3, v3
	v_max_f32_e32 v2, v2, v3
	v_cndmask_b32_e32 v3, v184, v186, vcc
	v_lshlrev_b32_e32 v3, 2, v3
	ds_bpermute_b32 v3, v3, v2
	s_waitcnt lgkmcnt(0)
	v_max_f32_e32 v3, v3, v3
	v_max_f32_e32 v2, v2, v3
	v_xor_b32_e32 v3, 16, v184
	v_cmp_lt_i32_e32 vcc, v3, v185
	s_nop 1
	v_cndmask_b32_e32 v3, v184, v3, vcc
	v_lshlrev_b32_e32 v3, 2, v3
	ds_bpermute_b32 v3, v3, v2
	v_cmp_gt_f32_e32 vcc, s3, v0
	s_mov_b32 s3, 0x42700000
	s_waitcnt lgkmcnt(0)
	v_max_f32_e32 v3, v3, v3
	v_max_f32_e32 v2, v2, v3
	ds_bpermute_b32 v3, v7, v2
	v_cndmask_b32_e32 v0, v0, v1, vcc
	v_sqrt_f32_e32 v1, v0
	s_waitcnt lgkmcnt(0)
	v_max_f32_e32 v3, v3, v3
	v_max_f32_e32 v2, v2, v3
	v_add_u32_e32 v3, -1, v1
	v_fma_f32 v4, -v3, v1, v0
	v_cmp_ge_f32_e64 s[40:41], 0, v4
	v_add_u32_e32 v4, 1, v1
	s_nop 0
	v_cndmask_b32_e64 v3, v1, v3, s[40:41]
	v_fma_f32 v1, -v4, v1, v0
	v_cmp_lt_f32_e64 s[40:41], 0, v1
	s_nop 1
	v_cndmask_b32_e64 v1, v3, v4, s[40:41]
	v_mul_f32_e32 v3, 0x37800000, v1
	v_cndmask_b32_e32 v1, v1, v3, vcc
	v_cmp_class_f32_e32 vcc, v0, v5
	s_nop 1
	v_cndmask_b32_e32 v0, v1, v0, vcc
	v_mul_f32_e32 v0, 0x413504f3, v0
	v_mul_f32_e32 v0, v2, v0
	v_mul_f32_e32 v0, 0x3f828f5c, v0
	v_mul_f32_e32 v0, 0x3e0293ee, v0
	v_cmp_gt_f32_e32 vcc, s3, v0
	v_ashrrev_i32_e32 v0, 4, v161
	v_and_b32_e32 v2, 0xfffff0, v0
	v_lshlrev_b32_e32 v3, 1, v0
	v_lshlrev_b32_e32 v1, 3, v161
	v_and_or_b32 v2, v3, 8, v2
	v_and_b32_e32 v35, 0x78, v1
	v_lshrrev_b32_e32 v3, 1, v0
	v_lshrrev_b32_e32 v2, 1, v2
	v_bfe_u32 v1, v1, 5, 2
	v_and_b32_e32 v4, 3, v0
	v_or_b32_e32 v2, v2, v1
	v_and_or_b32 v3, v3, 4, v4
	v_lshlrev_b32_e32 v164, 1, v35
	v_lshlrev_b32_e32 v2, 9, v2
	v_lshlrev_b32_e32 v3, 6, v3
	v_and_b32_e32 v4, 48, v164
	v_or3_b32 v20, v2, v3, v4
	v_add_u32_e32 v2, 32, v0
	v_and_b32_e32 v5, 0xfffff0, v2
	v_lshlrev_b32_e32 v6, 1, v2
	v_and_or_b32 v5, v6, 8, v5
	v_lshrrev_b32_e32 v5, 1, v5
	v_or_b32_e32 v1, v5, v1
	v_lshlrev_b32_e32 v1, 9, v1
	v_or3_b32 v21, v1, v3, v4
	v_ashrrev_i32_e32 v1, 31, v0
	v_ashrrev_i32_e32 v3, 31, v2
	v_lshlrev_b64 v[32:33], 8, v[0:1]
	v_lshlrev_b64 v[16:17], 8, v[2:3]
	v_or_b32_e32 v12, v32, v164
	v_mov_b32_e32 v13, v33
	v_or_b32_e32 v16, v16, v164
	v_lshl_add_u64 v[4:5], s[34:35], 0, v[12:13]
	v_lshl_add_u64 v[8:9], s[34:35], 0, v[16:17]
	v_lshl_add_u64 v[12:13], s[0:1], 0, v[12:13]
	v_lshl_add_u64 v[16:17], s[0:1], 0, v[16:17]
	global_load_dwordx4 v[4:7], v[4:5], off
	v_lshlrev_b32_e32 v0, 8, v0
	global_load_dwordx4 v[8:11], v[8:9], off
	v_and_b32_e32 v1, 0x70, v161
	global_load_dwordx4 v[12:15], v[12:13], off
	v_bitop3_b32 v202, v164, v0, v1 bitop3:0xde
	global_load_dwordx4 v[16:19], v[16:17], off
	v_lshlrev_b32_e32 v0, 8, v2
	v_bitop3_b32 v203, v164, v0, v1 bitop3:0xde
	v_lshlrev_b32_e32 v0, 4, v161
	v_and_b32_e32 v45, 0x70, v0
	v_bitop3_b32 v194, v162, v44, v45 bitop3:0xde
	v_add_u32_e32 v182, 0, v20
	v_add_u32_e32 v183, 0, v21
	v_add_u32_e32 v191, 0, v202
	v_add_u32_e32 v192, 0, v203
	v_add_u32_e32 v173, 0, v194
	s_waitcnt vmcnt(0)
	v_bitop3_b32 v195, v36, v44, v45 bitop3:0xde
	v_add_u32_e32 v174, 0, v195
	v_bitop3_b32 v196, v34, v44, v45 bitop3:0xde
	v_add_u32_e32 v175, 0, v196
	v_or_b32_e32 v34, 0x60, v162
	v_bitop3_b32 v197, v34, v44, v45 bitop3:0xde
	v_add_u32_e32 v177, 0, v197
	v_or_b32_e32 v34, 0x80, v162
	v_bitop3_b32 v198, v34, v44, v45 bitop3:0xde
	v_add_u32_e32 v178, 0, v198
	v_or_b32_e32 v34, 0xa0, v162
	v_bitop3_b32 v199, v34, v44, v45 bitop3:0xde
	v_add_u32_e32 v180, 0, v199
	v_or_b32_e32 v34, 0xc0, v162
	v_bitop3_b32 v200, v34, v44, v45 bitop3:0xde
	v_add_u32_e32 v181, 0, v200
	v_or_b32_e32 v34, 0xe0, v162
	v_bitop3_b32 v201, v34, v44, v45 bitop3:0xde
	v_add_u32_e32 v190, 0, v201
	s_cmp_lg_u64 vcc, exec
	s_cselect_b64 s[20:21], -1, 0
	s_cmp_eq_u64 vcc, exec
	s_waitcnt vmcnt(3)
	ds_write_b128 v182, v[4:7]
	s_waitcnt vmcnt(2)
	ds_write_b128 v183, v[8:11]
	s_waitcnt vmcnt(1)
	ds_write_b128 v191, v[12:15] offset:49152
	s_waitcnt vmcnt(0)
	ds_write_b128 v192, v[16:19] offset:49152
	s_waitcnt lgkmcnt(0)
	s_barrier
; __device__ __forceinline__ void partialSM(f32x16& p0, f32x16& p1, float& m_reg, float& mn, float& alpha, bool bounded) {
;   constexpr float THRL = THR * 1.4426950408889634f;
;   if (bounded) { mn = m_reg; alpha = 1.f; }
;   else {
;     float pmax = p0[0]; for (int r = 1; r < 16; ++r) pmax = fmaxf(pmax, p0[r]); for (int r = 0; r < 16; ++r) pmax = fmaxf(pmax, p1[r]);
;     { auto rr = __builtin_amdgcn_permlane32_swap(__float_as_uint(pmax), __float_as_uint(pmax), false, false);
;       pmax = fmaxf(__uint_as_float(rr[0]), __uint_as_float(rr[1])); }
;     if (__builtin_expect(__all(pmax - m_reg <= THRL), 1)) { mn = m_reg; alpha = 1.f; }
;     else { mn = fmaxf(m_reg, pmax); alpha = __builtin_amdgcn_exp2f(m_reg - mn); m_reg = mn; }
;     for (int r = 0; r < 16; ++r) p0[r] -= mn; for (int r = 0; r < 16; ++r) p1[r] -= mn;
; __device__ __forceinline__ void qkt(f32x16& p0, f32x16& p1, const bf16* Ks, const bf16x8* qr, int r32, int hi) {
;   p0 = f32x16{}; p1 = f32x16{};
;   for (int d0 = 0; d0 < 8; ++d0) { int cb = (d0 * 16 + hi * 8) * 2;
;     bf16x8 b0 = *reinterpret_cast<const bf16x8*>((const char*)Ks + KSWZ(r32, cb));
;     bf16x8 b1 = *reinterpret_cast<const bf16x8*>((const char*)Ks + KSWZ(32 + r32, cb));
;     p0 = __builtin_amdgcn_mfma_f32_32x32x16_bf16(b0, qr[d0], p0, 0, 0, 0);
;     p1 = __builtin_amdgcn_mfma_f32_32x32x16_bf16(b1, qr[d0], p1, 0, 0, 0); }
	ds_read_b128 v[0:3], v173 offset:49152
	ds_read_b128 v[4:7], v173 offset:57344
	s_waitcnt lgkmcnt(1)
	v_mfma_f32_32x32x16_bf16 v[16:31], v[0:3], v[112:115], 0
	ds_read_b128 v[36:39], v174 offset:49152
	ds_read_b128 v[40:43], v174 offset:57344
	s_waitcnt lgkmcnt(2)
	v_mfma_f32_32x32x16_bf16 v[0:15], v[4:7], v[112:115], 0
	s_waitcnt lgkmcnt(1)
	v_mfma_f32_32x32x16_bf16 v[16:31], v[36:39], v[116:119], v[16:31]
	s_waitcnt lgkmcnt(0)
	v_mfma_f32_32x32x16_bf16 v[0:15], v[40:43], v[116:119], v[0:15]
	ds_read_b128 v[36:39], v175 offset:49152
	ds_read_b128 v[40:43], v175 offset:57344
	s_waitcnt lgkmcnt(1)
	v_mfma_f32_32x32x16_bf16 v[16:31], v[36:39], v[120:123], v[16:31]
	s_waitcnt lgkmcnt(0)
	v_mfma_f32_32x32x16_bf16 v[0:15], v[40:43], v[120:123], v[0:15]
	ds_read_b128 v[36:39], v177 offset:49152
	ds_read_b128 v[40:43], v177 offset:57344
	s_waitcnt lgkmcnt(1)
	v_mfma_f32_32x32x16_bf16 v[16:31], v[36:39], v[124:127], v[16:31]
	s_waitcnt lgkmcnt(0)
	v_mfma_f32_32x32x16_bf16 v[0:15], v[40:43], v[124:127], v[0:15]
	ds_read_b128 v[36:39], v178 offset:49152
	ds_read_b128 v[40:43], v178 offset:57344
	s_waitcnt lgkmcnt(1)
	v_mfma_f32_32x32x16_bf16 v[16:31], v[36:39], v[128:131], v[16:31]
	s_waitcnt lgkmcnt(0)
	v_mfma_f32_32x32x16_bf16 v[0:15], v[40:43], v[128:131], v[0:15]
	ds_read_b128 v[36:39], v180 offset:49152
	ds_read_b128 v[40:43], v180 offset:57344
	s_waitcnt lgkmcnt(1)
	v_mfma_f32_32x32x16_bf16 v[16:31], v[36:39], v[132:135], v[16:31]
	s_waitcnt lgkmcnt(0)
	v_mfma_f32_32x32x16_bf16 v[0:15], v[40:43], v[132:135], v[0:15]
	ds_read_b128 v[36:39], v181 offset:49152
	ds_read_b128 v[40:43], v181 offset:57344
	s_waitcnt lgkmcnt(1)
	v_mfma_f32_32x32x16_bf16 v[16:31], v[36:39], v[136:139], v[16:31]
	s_waitcnt lgkmcnt(0)
	v_mfma_f32_32x32x16_bf16 v[0:15], v[40:43], v[136:139], v[0:15]
	ds_read_b128 v[36:39], v190 offset:49152
	ds_read_b128 v[40:43], v190 offset:57344
	s_waitcnt lgkmcnt(1)
	v_mfma_f32_32x32x16_bf16 v[16:31], v[36:39], v[140:143], v[16:31]
	s_waitcnt lgkmcnt(0)
	v_mfma_f32_32x32x16_bf16 v[0:15], v[40:43], v[140:143], v[0:15]
	s_cbranch_scc1 .LBB0_998
	s_nop 8
	v_max_f32_e32 v34, v17, v17
	v_max_f32_e32 v36, v16, v16
	v_max_f32_e32 v34, v36, v34
	v_max3_f32 v34, v34, v18, v19
	v_max3_f32 v34, v34, v20, v21
	v_max3_f32 v34, v34, v22, v23
	v_max3_f32 v34, v34, v24, v25
	v_max3_f32 v34, v34, v26, v27
	v_max3_f32 v34, v34, v28, v29
	v_max3_f32 v34, v34, v30, v31
	v_max3_f32 v34, v34, v0, v1
	v_max3_f32 v34, v34, v2, v3
	v_max3_f32 v34, v34, v4, v5
	v_max3_f32 v34, v34, v6, v7
	v_max3_f32 v34, v34, v8, v9
	v_max3_f32 v34, v34, v10, v11
	v_max3_f32 v34, v34, v12, v13
	v_max3_f32 v34, v34, v14, v15
	v_mov_b32_e32 v36, v34
	s_nop 1
	v_permlane32_swap_b32_e32 v34, v36
	v_max_f32_e32 v36, v36, v36
	v_max_f32_e32 v34, v34, v34
	v_max_f32_e32 v34, v34, v36
	v_add_f32_e32 v36, 0x7149f2ca, v34
	s_mov_b32 s3, 0x4138aa3b
	v_max_f32_e32 v34, 0xf149f2ca, v34
	v_cmp_ge_f32_e32 vcc, s3, v36
	v_sub_f32_e32 v36, 0xf149f2ca, v34
	v_exp_f32_e32 v36, v36
	s_cmp_eq_u64 vcc, exec
	v_mov_b32_e32 v37, 0xf149f2ca
	s_cselect_b64 vcc, -1, 0
	v_cndmask_b32_e32 v163, v34, v37, vcc
	v_mul_f32_e32 v34, 0, v36
	v_sub_f32_e32 v31, v31, v163
	v_sub_f32_e32 v30, v30, v163
	v_sub_f32_e32 v29, v29, v163
	v_sub_f32_e32 v28, v28, v163
	v_sub_f32_e32 v27, v27, v163
	v_sub_f32_e32 v26, v26, v163
	v_sub_f32_e32 v25, v25, v163
	v_sub_f32_e32 v24, v24, v163
	v_sub_f32_e32 v23, v23, v163
	v_sub_f32_e32 v22, v22, v163
	v_sub_f32_e32 v21, v21, v163
	v_sub_f32_e32 v20, v20, v163
	v_sub_f32_e32 v19, v19, v163
	v_sub_f32_e32 v18, v18, v163
	v_sub_f32_e32 v17, v17, v163
	v_sub_f32_e32 v16, v16, v163
	v_sub_f32_e32 v15, v15, v163
	v_sub_f32_e32 v14, v14, v163
	v_sub_f32_e32 v13, v13, v163
	v_sub_f32_e32 v12, v12, v163
	v_sub_f32_e32 v11, v11, v163
	v_sub_f32_e32 v10, v10, v163
	v_sub_f32_e32 v9, v9, v163
	v_sub_f32_e32 v8, v8, v163
	v_sub_f32_e32 v7, v7, v163
	v_sub_f32_e32 v6, v6, v163
	v_sub_f32_e32 v5, v5, v163
	v_sub_f32_e32 v4, v4, v163
	v_sub_f32_e32 v3, v3, v163
	v_sub_f32_e32 v2, v2, v163
	v_sub_f32_e32 v1, v1, v163
	v_sub_f32_e32 v0, v0, v163
	v_cndmask_b32_e64 v169, v34, 0, vcc
	s_branch .LBB0_999
